# speedup vs baseline: 1.0700x; 1.0119x over previous
.LBB0_141:
	s_waitcnt vmcnt(0)
	s_barrier
	s_and_saveexec_b64 s[0:1], s[46:47]
	s_cbranch_execz .LBB0_178
	v_mov_b32_e32 v0, 0x200e8
	ds_read2_b32 v[0:1], v0 offset1:2
	s_waitcnt lgkmcnt(0)
	v_readfirstlane_b32 s2, v0
	s_cmp_eq_u32 s2, 0
	s_cbranch_scc1 .Lslow_B
	v_readlane_b32 s2, v254, 2
	v_readlane_b32 s3, v254, 3
	v_and_b32_e32 v1, 7, v1
	v_lshlrev_b32_e32 v1, 8, v1
	s_add_u32 s2, s2, 0x480
	s_addc_u32 s3, s3, 0
	s_nop 4
	global_atomic_add v0, v1, v209, s[2:3] sc0
	s_waitcnt vmcnt(0)
	v_or_b32_e32 v0, 31, v0
	v_add_u32_e32 v0, 1, v0
	s_mov_b32 s5, 0
	s_nop 0
	v_readfirstlane_b32 s4, v0
	buffer_inv sc1

.Llb_B_done:
	s_waitcnt vmcnt(0)
	s_branch .LBB0_178

.LBB0_285:
	s_waitcnt vmcnt(0)
	s_barrier
	s_and_saveexec_b64 s[0:1], s[46:47]
	v_readlane_b32 s10, v254, 23
	s_mov_b64 s[12:13], 0x2000
	s_cbranch_execz .LBB0_322
	v_mov_b32_e32 v0, 0x200e8
	ds_read2_b32 v[0:1], v0 offset1:2
	ds_read_b32 v2, v0 offset:12
	s_waitcnt lgkmcnt(0)
	v_readfirstlane_b32 s2, v0
	s_nop 1
	s_cmp_eq_u32 s2, 0
	s_cbranch_scc1 .Lw1_slow
	v_readfirstlane_b32 s6, v2
	v_and_b32_e32 v1, 7, v1
	v_lshlrev_b32_e32 v2, 2, v1
	v_readlane_b32 s2, v254, 2
	v_readlane_b32 s3, v254, 3
	s_lshl_b32 s4, s98, 5
	s_addk_i32 s4, 0x3e40
	s_add_u32 s2, s2, s4
	s_addc_u32 s3, s3, 0
	s_mov_b32 s4, 0
	s_nop 2
	buffer_inv sc1

.Lw1_done:
	buffer_inv sc1
.Lw1f_done:
	s_waitcnt vmcnt(0)
.LBB0_322:
	s_or_b64 exec, exec, s[0:1]
	v_mov_b32_e32 v0, 0x20000
	s_barrier
	s_and_b32 s2, s98, 1
	v_add_u32_e32 v4, 0, v0
	ds_read_b64 v[6:7], v4 offset:216
	ds_read2_b64 v[0:3], v4 offset0:17 offset1:18
	s_mov_b32 s21, s57
	s_waitcnt lgkmcnt(0)
	v_readfirstlane_b32 s100, v6
	v_readfirstlane_b32 s101, v7
	s_nop 1
	s_sub_u32 s100, s100, 0xbb68100
	s_subb_u32 s101, s101, 0
	v_readfirstlane_b32 s0, v1
	s_nop 1
	v_writelane_b32 v254, s0, 43
	v_readfirstlane_b32 s0, v0
	v_readfirstlane_b32 s4, v3
	v_readfirstlane_b32 s5, v2
	ds_read2_b64 v[0:3], v4 offset0:24 offset1:28
	v_writelane_b32 v254, s0, 44
	s_lshl_b64 s[0:1], s[98:99], 5
	s_waitcnt lgkmcnt(0)
	v_readfirstlane_b32 s92, v2
	v_readfirstlane_b32 s93, v3
	s_add_u32 s0, s92, s0
	s_addc_u32 s1, s93, s1
	s_add_u32 s0, s0, 0xbb64080
	s_addc_u32 s1, s1, 0
	v_readlane_b32 s3, v254, 15
	s_nop 1
	s_and_b32 s3, s3, 7
	s_lshl_b32 s3, s3, 2
	s_add_u32 s0, s0, s3
	s_addc_u32 s1, s1, 0
	v_writelane_b32 v254, s0, 47
	s_bitcmp1_b32 s98, 0
	s_cselect_b64 s[96:97], -1, 0
	v_writelane_b32 v254, s1, 48
	s_add_u32 s0, s92, 0x20b68100
	v_writelane_b32 v254, s0, 39
	s_addc_u32 s0, s93, 0
	v_writelane_b32 v254, s0, 41
	s_add_u32 s0, s92, 0x9000000
	v_writelane_b32 v254, s0, 49
	s_addc_u32 s0, s93, 0
	v_writelane_b32 v254, s0, 50
	s_add_u32 s0, s92, 0xa000000
	v_writelane_b32 v254, s0, 51
	s_addc_u32 s0, s93, 0
	v_writelane_b32 v254, s0, 52
	s_add_u32 s0, s92, 0x22b68100
	v_writelane_b32 v254, s0, 42
	s_addc_u32 s0, s93, 0
	v_writelane_b32 v254, s0, 45
	s_add_u32 s0, s92, 0x27b68100
	v_writelane_b32 v254, s0, 53
	s_addc_u32 s0, s93, 0
	v_writelane_b32 v254, s0, 54
	s_add_u32 s0, s92, 0x24b68100
	v_writelane_b32 v254, s0, 46
	s_addc_u32 s0, s93, 0
	v_writelane_b32 v254, s0, 37
	s_and_b32 s0, s98, 2
	v_writelane_b32 v254, s0, 55
	s_add_u32 s0, s92, 0xb000000
	v_writelane_b32 v254, s0, 56
	s_addc_u32 s0, s93, 0
	v_writelane_b32 v254, s0, 57
	s_add_u32 s0, s92, 0xb400000
	v_writelane_b32 v254, s0, 58
	s_addc_u32 s0, s93, 0
	v_writelane_b32 v254, s0, 59
	s_add_u32 s0, s92, 0x26b68100
	v_writelane_b32 v254, s0, 60
	s_addc_u32 s0, s93, 0
	v_writelane_b32 v254, s0, 61
	s_add_u32 s0, s92, 0x27368100
	v_writelane_b32 v254, s0, 62
	s_addc_u32 s0, s93, 0
	v_writelane_b32 v254, s0, 63
	s_add_u32 s0, s92, 0x8800000
	v_writelane_b32 v254, s0, 31
	s_addc_u32 s0, s93, 0
	v_writelane_b32 v254, s0, 33
	s_add_u32 s0, s92, 0x8c00000
	v_writelane_b32 v254, s0, 34
	s_addc_u32 s0, s93, 0
	v_writelane_b32 v254, s0, 30
	s_lshl_b32 s0, s20, 3
	v_writelane_b32 v254, s0, 35
	s_add_u32 s0, s100, 0xbb68100
	v_writelane_b32 v254, s0, 36
	s_addc_u32 s0, s101, 0
	v_writelane_b32 v255, s0, 0
	s_lshl_b32 s0, s2, 10
	s_cmp_eq_u32 s2, 0
	v_writelane_b32 v255, s0, 1
	s_cselect_b64 s[0:1], -1, 0
	v_writelane_b32 v255, s0, 2
	v_readfirstlane_b32 s7, v0
	v_readfirstlane_b32 s6, v1
	v_writelane_b32 v255, s1, 3
	s_and_b64 s[0:1], s[0:1], exec
	s_movk_i32 s0, 0x1600
	s_cselect_b32 s0, 0x600, s0
	s_add_u32 s48, s92, 0x13b68100
	s_addc_u32 s49, s93, 0
	v_writelane_b32 v255, s0, 4
	s_add_u32 s0, s92, 0x29b68100
	s_addc_u32 s1, s93, 0
	v_writelane_b32 v255, s0, 5
	s_lshl_b32 s56, s20, 8
	v_mov_b32_e32 v0, v208
	v_writelane_b32 v255, s1, 6
	s_lshl_b64 s[0:1], s[56:57], 2
	s_add_u32 s2, s92, s0
	s_addc_u32 s3, s93, s1
	s_add_u32 s2, s2, 0xbb67700
	v_writelane_b32 v255, s2, 7
	s_addc_u32 s2, s3, 0
	v_writelane_b32 v255, s2, 8
	s_lshl_b64 s[2:3], s[20:21], 2
	s_add_u32 s2, s92, s2
	s_addc_u32 s3, s93, s3
	s_add_u32 s2, s2, 0xbb64000
	s_addc_u32 s3, s3, 0
	s_cmp_lt_u32 s98, 2
	v_writelane_b32 v255, s2, 9
	s_cselect_b64 vcc, -1, 0
	s_add_u32 s0, s7, s0
	v_writelane_b32 v255, s3, 10
	s_addc_u32 s1, s6, s1
	v_writelane_b32 v255, s0, 11
	s_mov_b32 s2, s20
	s_nop 0
	v_writelane_b32 v255, s1, 12
	v_writelane_b32 v255, s2, 13
	s_mul_i32 s1, s20, 0x3000
	s_mul_hi_u32 s0, s20, 0x3000
	v_writelane_b32 v255, s3, 14
	s_add_u32 s2, s5, s1
	s_addc_u32 s3, s4, s0
	v_writelane_b32 v255, s2, 15
	v_cmp_eq_u32_e64 s[14:15], 0, v0
	v_mov_b32_e32 v0, 0x3ee34c56
	v_writelane_b32 v255, s3, 16
	v_writelane_b32 v255, s14, 17
	v_cndmask_b32_e32 v97, v0, v219, vcc
	s_nop 0
	v_writelane_b32 v255, s15, 18
	s_mov_b32 s0, 0
	s_nop 0
	v_writelane_b32 v255, s0, 40
	s_branch .LBB0_325

.Ltq_done:
	s_cmpk_gt_i32 s6, 0x3ff
	s_cbranch_scc1 .LBB0_324
	s_cmpk_lt_i32 s6, 0x100
	s_cbranch_scc1 .Lw2_skip
	v_readlane_b32 s2, v255, 40
	s_nop 1
	s_cmp_lg_u32 s2, 0
	s_cbranch_scc1 .Lw2_skip
	s_and_saveexec_b64 vcc, s[14:15]
	s_cbranch_execz .Lw2_join
	v_mov_b32_e32 v0, 0x200e8
	ds_read2_b32 v[0:1], v0 offset1:2
	v_readlane_b32 s2, v254, 2
	v_readlane_b32 s3, v254, 3
	v_readlane_b32 s4, v254, 28
	s_waitcnt lgkmcnt(0)
	v_readfirstlane_b32 s5, v0
	s_nop 1
	s_cmp_eq_u32 s5, 0
	s_cbranch_scc1 .Lw2_slowaddr
	v_and_b32_e32 v1, 7, v1
	v_lshlrev_b32_e32 v1, 2, v1
	v_mov_b32_e32 v2, 16
	s_lshl_b32 s4, s4, 5
	s_addk_i32 s4, 0x3ec0
	buffer_inv sc1
	s_branch .Lw2_addr

.Lw2_done:
	v_cmp_eq_u32_e64 s[2:3], 16, v2
	s_nop 1
	s_cmp_lg_u64 s[2:3], 0
	s_cbranch_scc1 .Lw2_noinv
	buffer_inv sc1
.Lw2_noinv:
	s_waitcnt vmcnt(0)
.Lw2_join:
	s_or_b64 exec, exec, vcc
	s_barrier
	s_mov_b32 s2, 1
	s_nop 0
	v_writelane_b32 v255, s2, 40

.LBB0_493:
	s_waitcnt vmcnt(0)
	v_cmp_eq_u32_e32 vcc, 0, v6
	s_waitcnt vmcnt(63) expcnt(7) lgkmcnt(15)
	s_barrier
	s_and_saveexec_b64 s[6:7], vcc
	s_cbranch_execz .LBB0_499
	v_mov_b32_e32 v0, 0x200e8
	ds_read_b32 v0, v0
	s_waitcnt lgkmcnt(0)
	v_readfirstlane_b32 s8, v0
	s_nop 1
	s_cmp_lg_u32 s8, 0
	s_cbranch_scc1 .Lpub_fast
	buffer_wbl2 sc1
.Lpub_fast:
	s_mov_b64 s[8:9], exec
	s_waitcnt vmcnt(0)
	s_waitcnt vmcnt(0)
	v_mbcnt_lo_u32_b32 v0, s8, 0
	v_mbcnt_hi_u32_b32 v0, s9, v0
	v_cmp_eq_u32_e32 vcc, 0, v0
	s_and_saveexec_b64 s[10:11], vcc
	s_cbranch_execz .LBB0_496
	s_ashr_i32 s3, s2, 31
	s_lshl_b64 s[14:15], s[2:3], 2
	v_readlane_b32 s3, v255, 7
	s_add_u32 s14, s3, s14
	v_readlane_b32 s3, v255, 8
	s_addc_u32 s15, s3, s15
	s_bcnt1_i32_b64 s3, s[8:9]
	v_mov_b32_e32 v1, s3
	global_atomic_add v1, v175, v1, s[14:15] sc0

.LBB0_506:
	s_waitcnt vmcnt(0)
	v_readlane_b32 s46, v254, 0
	v_readlane_b32 s47, v254, 1
	s_waitcnt vmcnt(63) expcnt(7) lgkmcnt(15)
	s_barrier
	s_and_saveexec_b64 s[0:1], s[46:47]
	v_readlane_b32 s49, v254, 4
	v_readlane_b32 s30, v254, 24
	s_mov_b32 s31, 0xc000
	s_mov_b32 s33, 0xe000
	s_mov_b32 s34, 0xf000
	s_cbranch_execz .LBB0_543
	s_cmp_eq_u32 s98, 3
	s_cbranch_scc1 .Lslow_C
	v_mov_b32_e32 v0, 0x200e8
	ds_read2_b32 v[0:1], v0 offset1:2
	s_waitcnt lgkmcnt(0)
	v_readfirstlane_b32 s2, v0
	s_cmp_eq_u32 s2, 0
	s_cbranch_scc1 .Lslow_C
	v_readlane_b32 s2, v254, 2
	v_readlane_b32 s3, v254, 3
	v_and_b32_e32 v1, 7, v1
	v_lshlrev_b32_e32 v1, 8, v1
	s_add_u32 s2, s2, 0x480
	s_addc_u32 s3, s3, 0
	s_nop 4
	global_atomic_add v0, v1, v209, s[2:3] sc0
	s_waitcnt vmcnt(0)
	v_or_b32_e32 v0, 31, v0
	v_add_u32_e32 v0, 1, v0
	s_mov_b32 s5, 0
	s_nop 0
	v_readfirstlane_b32 s4, v0
	buffer_inv sc1

.LBB0_560:
	s_cmp_eq_u32 s98, 3
	s_cbranch_scc1 .LBB0_131
	s_waitcnt vmcnt(0)
	s_barrier
	s_and_saveexec_b64 s[0:1], s[46:47]
	s_cbranch_execz .LBB0_130
	v_mov_b32_e32 v0, 0x200e8
	ds_read2_b32 v[0:1], v0 offset1:2
	s_waitcnt lgkmcnt(0)
	v_readfirstlane_b32 s2, v0
	s_cmp_eq_u32 s2, 0
	s_cbranch_scc1 .Lslow_A
	v_readlane_b32 s2, v254, 2
	v_readlane_b32 s3, v254, 3
	v_and_b32_e32 v1, 7, v1
	v_lshlrev_b32_e32 v1, 8, v1
	s_add_u32 s2, s2, 0x480
	s_addc_u32 s3, s3, 0
	s_nop 4
	global_atomic_add v0, v1, v209, s[2:3] sc0
	s_waitcnt vmcnt(0)
	v_or_b32_e32 v0, 31, v0
	v_add_u32_e32 v0, 1, v0
	s_mov_b32 s5, 0
	s_nop 0
	v_readfirstlane_b32 s4, v0
	buffer_inv sc1
